# attention A loop: per-step copies of the -m accumulator seed removed (QK MFMAs read it from one register block; copied once for the tail step)
# speedup vs baseline: 1.0104x; 1.0049x over previous
; template <int OFF> __device__ __forceinline__ s16x4 tr_read(int vb) { s16x4 r; asm volatile("ds_read_b64_tr_b16 %0, %1 offset:%2" : "=&v"(r) : "v"(vb), "i"(OFF) : "memory"); return r; }
; __device__ __forceinline__ void finishSM(f32x16& p0, f32x16& p1, float alpha, float& l_reg, bf16x8& pa0, bf16x8& pa1, bf16x8& pa2, bf16x8& pa3) {
; #pragma unroll
;   for (int r = 0; r < 16; ++r) p1[r] = __builtin_amdgcn_exp2f(p1[r]);
;   float ps = 0;
; #pragma unroll
;   for (int r = 0; r < 16; ++r) ps += p0[r];
; #pragma unroll
;   for (int r = 0; r < 16; ++r) ps += p1[r];
;   { auto rr = __builtin_amdgcn_permlane32_swap(__float_as_uint(ps), __float_as_uint(ps), false, false);
;     ps = __uint_as_float(rr[0]) + __uint_as_float(rr[1]); }
;   l_reg = l_reg * alpha + ps;
;     ...
;   ATT_PKN(p0, 0, pa0); ATT_PKN(p0, 8, pa1); ATT_PKN(p1, 0, pa2); ATT_PKN(p1, 8, pa3);
;     ...
; }
; __device__ __forceinline__ void qkt(f32x16& p0, f32x16& p1, const bf16* Ks, const bf16x8* qr, int r32, int hi, int mp, const f32x16& negm) {
; #pragma unroll
;   for (int d0 = 0; d0 < 4; ++d0) { int cb = ((mp * 4 + d0) * 16 + hi * 8) * 2;
;     bf16x8 b0 = *reinterpret_cast<const bf16x8*>((const char*)Ks + KSWZ(r32, cb));
;     bf16x8 b1 = *reinterpret_cast<const bf16x8*>((const char*)Ks + KSWZ(32 + r32, cb));
;     if (d0 == 0) { p0 = __builtin_amdgcn_mfma_f32_32x32x16_bf16(b0, qr[0], negm, 0, 0, 0); p1 = __builtin_amdgcn_mfma_f32_32x32x16_bf16(b1, qr[0], negm, 0, 0, 0); }
;     else { p0 = __builtin_amdgcn_mfma_f32_32x32x16_bf16(b0, qr[d0], p0, 0, 0, 0); p1 = __builtin_amdgcn_mfma_f32_32x32x16_bf16(b1, qr[d0], p1, 0, 0, 0); } }
; }
; __device__ __forceinline__ int v_st(int k, int c) { const int kk = k; return ((kk >> 3) * 4 + (c >> 5)) * 512 + ((kk & 7) * 32 + (c & 31)) * 2; }
; template <int D0> __device__ __forceinline__ void pv_one(f32x16& od, int vb, bf16x8 pa0, bf16x8 pa1, bf16x8 pa2, bf16x8 pa3) {
;   const s16x4 l0 = tr_read<v_rd_off(D0, 0, 0)>(vb), h0 = tr_read<v_rd_off(D0, 0, 1)>(vb), l1 = tr_read<v_rd_off(D0, 1, 0)>(vb), h1 = tr_read<v_rd_off(D0, 1, 1)>(vb);
;   const s16x4 l2 = tr_read<v_rd_off(D0, 2, 0)>(vb), h2 = tr_read<v_rd_off(D0, 2, 1)>(vb), l3 = tr_read<v_rd_off(D0, 3, 0)>(vb), h3 = tr_read<v_rd_off(D0, 3, 1)>(vb);
.LBB0_197:
	s_add_i32 s10, s39, 0
	v_add_u32_e32 v112, s10, v202
	ds_read_b128 v[236:239], v112 offset:24576
	ds_read_b128 v[112:115], v112 offset:16384
	v_add_u32_e32 v208, s10, v201
	ds_read_b128 v[68:71], v208 offset:24576
	ds_read_b128 v[72:75], v208 offset:16384
	v_add_u32_e32 v208, s10, v199
	v_exp_f32_e32 v210, v96
	v_add_f32_e32 v96, 0, v172
	v_add_f32_e32 v96, v174, v96
	s_waitcnt lgkmcnt(2)
	v_mfma_f32_32x32x16_bf16 v[128:143], v[112:115], v[158:161], v[80:95]
	v_add_f32_e32 v96, v175, v96
	v_add_f32_e32 v96, v211, v96
	v_mfma_f32_32x32x16_bf16 v[112:127], v[236:239], v[158:161], v[80:95]
	ds_read_b128 v[236:239], v208 offset:24576
	ds_read_b128 v[240:243], v208 offset:16384
	v_add_u32_e32 v208, s10, v183
	v_add_f32_e32 v96, v212, v96
	v_add_f32_e32 v96, v215, v96
	v_add_f32_e32 v96, v216, v96
	v_add_f32_e32 v96, v233, v96
	v_add_f32_e32 v96, v173, v96
	s_waitcnt lgkmcnt(2)
	v_mfma_f32_32x32x16_bf16 v[112:127], v[68:71], v[154:157], v[112:127]
	v_add_f32_e32 v96, v176, v96
	v_add_f32_e32 v96, v177, v96
	v_add_f32_e32 v96, v213, v96
	v_add_f32_e32 v96, v214, v96
	v_exp_f32_e32 v235, v97
	v_add_f32_e32 v96, v217, v96
	v_add_f32_e32 v96, v232, v96
	v_mfma_f32_32x32x16_bf16 v[128:143], v[72:75], v[154:157], v[128:143]
	ds_read_b128 v[68:71], v208 offset:24576
	ds_read_b128 v[72:75], v208 offset:16384
	v_add_f32_e32 v96, v234, v96
	v_add_f32_e32 v96, v210, v96
	v_add_f32_e32 v96, v235, v96
	v_exp_f32_e32 v244, v106
	v_exp_f32_e32 v245, v107
	s_waitcnt lgkmcnt(2)
	v_mfma_f32_32x32x16_bf16 v[112:127], v[236:239], v[150:153], v[112:127]
	v_exp_f32_e32 v246, v108
	v_exp_f32_e32 v247, v109
	v_exp_f32_e32 v248, v110
	v_exp_f32_e32 v111, v111
	v_cvt_pk_bf16_f32 v97, v175, v211
	v_cvt_pk_bf16_f32 v109, v244, v245
	v_cvt_pk_bf16_f32 v110, v246, v247
	v_mfma_f32_32x32x16_bf16 v[128:143], v[240:243], v[150:153], v[128:143]
	s_waitcnt lgkmcnt(0)
	v_mfma_f32_32x32x16_bf16 v[112:127], v[68:71], v[146:149], v[112:127]
	v_exp_f32_e32 v236, v98
	v_exp_f32_e32 v237, v99
	v_exp_f32_e32 v238, v100
	v_exp_f32_e32 v239, v101
	v_add_f32_e32 v96, v236, v96
	v_add_f32_e32 v96, v237, v96
	v_add_f32_e32 v96, v238, v96
	v_mfma_f32_32x32x16_bf16 v[128:143], v[72:75], v[146:149], v[128:143]
	v_exp_f32_e32 v240, v102
	v_exp_f32_e32 v241, v103
	v_exp_f32_e32 v242, v104
	v_exp_f32_e32 v243, v105
	v_add_f32_e32 v96, v239, v96
	v_add_f32_e32 v96, v240, v96
	v_add_f32_e32 v96, v241, v96
	v_add_f32_e32 v96, v242, v96
	v_add_f32_e32 v96, v243, v96
	v_add_f32_e32 v96, v244, v96
	v_add_f32_e32 v96, v245, v96
	v_add_f32_e32 v96, v246, v96
	v_add_f32_e32 v96, v247, v96
	v_add_f32_e32 v96, v248, v96
	v_add_f32_e32 v208, v111, v96
	v_mov_b32_e32 v209, v208
	s_nop 1
	v_permlane32_swap_b32_e32 v208, v209
	v_cvt_pk_bf16_f32 v96, v172, v174
	v_cvt_pk_bf16_f32 v98, v212, v215
	v_cvt_pk_bf16_f32 v99, v216, v233
	v_cvt_pk_bf16_f32 v100, v173, v176
	v_cvt_pk_bf16_f32 v101, v177, v213
	v_cvt_pk_bf16_f32 v102, v214, v217
	v_cvt_pk_bf16_f32 v103, v232, v234
	v_cvt_pk_bf16_f32 v104, v210, v235
	v_cvt_pk_bf16_f32 v105, v236, v237
	v_cvt_pk_bf16_f32 v106, v238, v239
	v_cvt_pk_bf16_f32 v107, v240, v241
	v_cvt_pk_bf16_f32 v108, v242, v243
	v_cvt_pk_bf16_f32 v111, v248, v111
	v_add_u32_e32 v240, s48, v205
	ds_read_b64_tr_b16 v[210:211], v240 offset:0
	ds_read_b64_tr_b16 v[212:213], v240 offset:0x800
	ds_read_b64_tr_b16 v[214:215], v240 offset:0x1000
	ds_read_b64_tr_b16 v[216:217], v240 offset:0x1800
	ds_read_b64_tr_b16 v[232:233], v240 offset:0x2000
	ds_read_b64_tr_b16 v[234:235], v240 offset:0x2800
	ds_read_b64_tr_b16 v[236:237], v240 offset:0x3000
	ds_read_b64_tr_b16 v[238:239], v240 offset:0x3800
	v_lshl_add_u64 v[174:175], s[50:51], 0, v[168:169]
	s_add_i32 s12, s21, s56
	v_lshl_add_u64 v[172:173], v[174:175], 0, s[36:37]
	s_add_i32 m0, s12, 0x4000
	s_mov_b64 s[10:11], 0x4030000
	global_load_lds_dwordx4 v[172:173], off
	v_lshl_add_u64 v[172:173], s[50:51], 0, v[188:189]
	v_lshl_add_u64 v[176:177], v[172:173], 0, s[10:11]
	s_mov_b32 m0, s12
	s_mov_b64 s[10:11], 0x4030080
	global_load_lds_dwordx4 v[176:177], off
	v_lshl_add_u64 v[176:177], s[50:51], 0, v[170:171]
	v_lshl_add_u64 v[66:67], v[176:177], 0, s[36:37]
	s_add_i32 m0, s12, 0x4400
	s_nop 0
	global_load_lds_dwordx4 v[66:67], off
	v_lshl_add_u64 v[66:67], v[172:173], 0, s[10:11]
	s_add_i32 m0, s12, 0x400
	s_nop 0
	global_load_lds_dwordx4 v[66:67], off
	s_waitcnt lgkmcnt(0)
; #define SBAR() __builtin_amdgcn_sched_barrier(0)
; template <int OFF> __device__ __forceinline__ s16x4 tr_read(int vb) { s16x4 r; asm volatile("ds_read_b64_tr_b16 %0, %1 offset:%2" : "=&v"(r) : "v"(vb), "i"(OFF) : "memory"); return r; }
; template <bool FIRST> __device__ __forceinline__ void partialSM(f32x16& p0, f32x16& p1, float& m_reg, f32x16& negm, float& alpha) {
;   float pmax = p0[0];
; #pragma unroll
;   for (int r = 1; r < 16; ++r) pmax = fmaxf(pmax, p0[r]);
; #pragma unroll
;   for (int r = 0; r < 16; ++r) pmax = fmaxf(pmax, p1[r]);
;   { auto rr = __builtin_amdgcn_permlane32_swap(__float_as_uint(pmax), __float_as_uint(pmax), false, false);
;     pmax = fmaxf(__uint_as_float(rr[0]), __uint_as_float(rr[1])); }
;   alpha = 1.f;
;   if (FIRST || __builtin_expect(__any(pmax > THR), 0)) { const float dl = FIRST ? pmax : fmaxf(pmax, 0.f); m_reg += dl; if (!FIRST) alpha = __builtin_amdgcn_exp2f(-dl);
; template <int D0> __device__ __forceinline__ void pv_one(f32x16& od, int vb, bf16x8 pa0, bf16x8 pa1, bf16x8 pa2, bf16x8 pa3) {
;   const s16x4 l0 = tr_read<v_rd_off(D0, 0, 0)>(vb), h0 = tr_read<v_rd_off(D0, 0, 1)>(vb), l1 = tr_read<v_rd_off(D0, 1, 0)>(vb), h1 = tr_read<v_rd_off(D0, 1, 1)>(vb);
;   const s16x4 l2 = tr_read<v_rd_off(D0, 2, 0)>(vb), h2 = tr_read<v_rd_off(D0, 2, 1)>(vb), l3 = tr_read<v_rd_off(D0, 3, 0)>(vb), h3 = tr_read<v_rd_off(D0, 3, 1)>(vb);
;   asm volatile("s_waitcnt lgkmcnt(0)" ::: "memory"); SBAR();
;   od = __builtin_amdgcn_mfma_f32_32x32x16_bf16(pa0, ATT_PK(l0, h0), od, 0, 0, 0);
;   od = __builtin_amdgcn_mfma_f32_32x32x16_bf16(pa1, ATT_PK(l1, h1), od, 0, 0, 0);
;   od = __builtin_amdgcn_mfma_f32_32x32x16_bf16(pa2, ATT_PK(l2, h2), od, 0, 0, 0);
;   od = __builtin_amdgcn_mfma_f32_32x32x16_bf16(pa3, ATT_PK(l3, h3), od, 0, 0, 0);
; }
; __device__ __forceinline__ void pv_d0(f32x16* o, int vb, bf16x8 pa0, bf16x8 pa1, bf16x8 pa2, bf16x8 pa3) {
;   pv_one<0>(o[0], vb, pa0, pa1, pa2, pa3); pv_one<1>(o[1], vb, pa0, pa1, pa2, pa3); pv_one<2>(o[2], vb, pa0, pa1, pa2, pa3); pv_one<3>(o[3], vb, pa0, pa1, pa2, pa3);
; }
	s_nop 0
	v_mfma_f32_32x32x16_bf16 v[0:15], v[96:99], v[210:213], v[0:15]
	ds_read_b64_tr_b16 v[210:211], v240 offset:0x200
	ds_read_b64_tr_b16 v[212:213], v240 offset:0xa00
	v_mfma_f32_32x32x16_bf16 v[0:15], v[100:103], v[214:217], v[0:15]
	ds_read_b64_tr_b16 v[214:215], v240 offset:0x1200
	ds_read_b64_tr_b16 v[216:217], v240 offset:0x1a00
	v_mfma_f32_32x32x16_bf16 v[0:15], v[104:107], v[232:235], v[0:15]
	ds_read_b64_tr_b16 v[232:233], v240 offset:0x2200
	ds_read_b64_tr_b16 v[234:235], v240 offset:0x2a00
	v_mfma_f32_32x32x16_bf16 v[0:15], v[108:111], v[236:239], v[0:15]
	ds_read_b64_tr_b16 v[236:237], v240 offset:0x3200
	ds_read_b64_tr_b16 v[238:239], v240 offset:0x3a00
	s_waitcnt lgkmcnt(0)
	v_mfma_f32_32x32x16_bf16 v[48:63], v[96:99], v[210:213], v[48:63]
	ds_read_b64_tr_b16 v[210:211], v240 offset:0x400
	ds_read_b64_tr_b16 v[212:213], v240 offset:0xc00
	v_mfma_f32_32x32x16_bf16 v[48:63], v[100:103], v[214:217], v[48:63]
	ds_read_b64_tr_b16 v[214:215], v240 offset:0x1400
	ds_read_b64_tr_b16 v[216:217], v240 offset:0x1c00
	v_mfma_f32_32x32x16_bf16 v[48:63], v[104:107], v[232:235], v[48:63]
	ds_read_b64_tr_b16 v[232:233], v240 offset:0x2400
	ds_read_b64_tr_b16 v[234:235], v240 offset:0x2c00
	v_mfma_f32_32x32x16_bf16 v[48:63], v[108:111], v[236:239], v[48:63]
	ds_read_b64_tr_b16 v[236:237], v240 offset:0x3400
	ds_read_b64_tr_b16 v[238:239], v240 offset:0x3c00
	s_waitcnt lgkmcnt(0)
	v_mfma_f32_32x32x16_bf16 v[32:47], v[96:99], v[210:213], v[32:47]
	ds_read_b64_tr_b16 v[210:211], v240 offset:0x600
	ds_read_b64_tr_b16 v[212:213], v240 offset:0xe00
	v_mfma_f32_32x32x16_bf16 v[32:47], v[100:103], v[214:217], v[32:47]
	ds_read_b64_tr_b16 v[214:215], v240 offset:0x1600
	ds_read_b64_tr_b16 v[216:217], v240 offset:0x1e00
	v_mfma_f32_32x32x16_bf16 v[32:47], v[104:107], v[232:235], v[32:47]
	ds_read_b64_tr_b16 v[232:233], v240 offset:0x2600
	ds_read_b64_tr_b16 v[234:235], v240 offset:0x2e00
	v_mfma_f32_32x32x16_bf16 v[32:47], v[108:111], v[236:239], v[32:47]
	ds_read_b64_tr_b16 v[236:237], v240 offset:0x3600
	ds_read_b64_tr_b16 v[238:239], v240 offset:0x3e00
	s_waitcnt lgkmcnt(0)
	v_mfma_f32_32x32x16_bf16 v[16:31], v[96:99], v[210:213], v[16:31]
	v_max_f32_e32 v96, v129, v129
	v_max_f32_e32 v97, v128, v128
	v_max_f32_e32 v96, v97, v96
	v_max3_f32 v96, v96, v130, v131
	v_max3_f32 v96, v96, v132, v133
	v_max3_f32 v96, v96, v134, v135
	v_max3_f32 v96, v96, v136, v137
	v_mfma_f32_32x32x16_bf16 v[16:31], v[100:103], v[214:217], v[16:31]
	v_max3_f32 v96, v96, v138, v139
	v_max3_f32 v96, v96, v140, v141
	v_max3_f32 v96, v96, v142, v143
	v_max3_f32 v96, v96, v112, v113
	v_max3_f32 v96, v96, v114, v115
	v_max3_f32 v96, v96, v116, v117
	v_max3_f32 v96, v96, v118, v119
	v_mfma_f32_32x32x16_bf16 v[16:31], v[104:107], v[232:235], v[16:31]
	v_max3_f32 v96, v96, v120, v121
	v_max3_f32 v96, v96, v122, v123
	v_max3_f32 v96, v96, v124, v125
	v_max3_f32 v96, v96, v126, v127
	v_mov_b32_e32 v97, v96
	s_nop 1
	v_permlane32_swap_b32_e32 v96, v97
	v_mfma_f32_32x32x16_bf16 v[16:31], v[108:111], v[236:239], v[16:31]
	v_max_f32_e32 v97, v97, v97
	v_max_f32_e32 v96, v96, v96
	v_max_f32_e32 v96, v96, v97
	v_cmp_lt_f32_e32 vcc, s19, v96
	s_cbranch_vccnz .LBB0_215
	v_mov_b32_e32 v210, 1.0
	v_cmp_gt_f32_e32 vcc, 1.0, v210
	s_cbranch_vccz .LBB0_202

; template <bool FIRST> __device__ __forceinline__ void partialSM(f32x16& p0, f32x16& p1, float& m_reg, f32x16& negm, float& alpha) {
;     ...
;   for (int r = 0; r < 16; ++r) p0[r] = __builtin_amdgcn_exp2f(p0[r]);
; }
; __device__ __forceinline__ void finishSM(f32x16& p0, f32x16& p1, float alpha, float& l_reg, bf16x8& pa0, bf16x8& pa1, bf16x8& pa2, bf16x8& pa3) {
; #pragma unroll
;   for (int r = 0; r < 16; ++r) p1[r] = __builtin_amdgcn_exp2f(p1[r]);
;   float ps = 0;
; #pragma unroll
;   for (int r = 0; r < 16; ++r) ps += p0[r];
; #pragma unroll
;   for (int r = 0; r < 16; ++r) ps += p1[r];
;   { auto rr = __builtin_amdgcn_permlane32_swap(__float_as_uint(ps), __float_as_uint(ps), false, false);
;     ps = __uint_as_float(rr[0]) + __uint_as_float(rr[1]); }
;   l_reg = l_reg * alpha + ps;
;     ...
;   ATT_PKN(p0, 0, pa0); ATT_PKN(p0, 8, pa1); ATT_PKN(p1, 0, pa2); ATT_PKN(p1, 8, pa3);
;     ...
; }
; __device__ __forceinline__ void qkt(f32x16& p0, f32x16& p1, const bf16* Ks, const bf16x8* qr, int r32, int hi, int mp, const f32x16& negm) {
; #pragma unroll
;   for (int d0 = 0; d0 < 4; ++d0) { int cb = ((mp * 4 + d0) * 16 + hi * 8) * 2;
;     bf16x8 b0 = *reinterpret_cast<const bf16x8*>((const char*)Ks + KSWZ(r32, cb));
;     bf16x8 b1 = *reinterpret_cast<const bf16x8*>((const char*)Ks + KSWZ(32 + r32, cb));
;     if (d0 == 0) { p0 = __builtin_amdgcn_mfma_f32_32x32x16_bf16(b0, qr[0], negm, 0, 0, 0); p1 = __builtin_amdgcn_mfma_f32_32x32x16_bf16(b1, qr[0], negm, 0, 0, 0); }
;     else { p0 = __builtin_amdgcn_mfma_f32_32x32x16_bf16(b0, qr[d0], p0, 0, 0, 0); p1 = __builtin_amdgcn_mfma_f32_32x32x16_bf16(b1, qr[d0], p1, 0, 0, 0); } }
; }
; __device__ __forceinline__ int v_st(int k, int c) { const int kk = k; return ((kk >> 3) * 4 + (c >> 5)) * 512 + ((kk & 7) * 32 + (c & 31)) * 2; }
; template <int D0> __device__ __forceinline__ void pv_one(f32x16& od, int vb, bf16x8 pa0, bf16x8 pa1, bf16x8 pa2, bf16x8 pa3) {
;   const s16x4 l0 = tr_read<v_rd_off(D0, 0, 0)>(vb), h0 = tr_read<v_rd_off(D0, 0, 1)>(vb), l1 = tr_read<v_rd_off(D0, 1, 0)>(vb), h1 = tr_read<v_rd_off(D0, 1, 1)>(vb);
;   const s16x4 l2 = tr_read<v_rd_off(D0, 2, 0)>(vb), h2 = tr_read<v_rd_off(D0, 2, 1)>(vb), l3 = tr_read<v_rd_off(D0, 3, 0)>(vb), h3 = tr_read<v_rd_off(D0, 3, 1)>(vb);
.LBB0_202:
	v_exp_f32_e32 v211, v128
	v_exp_f32_e32 v213, v129
	v_exp_f32_e32 v214, v130
	v_exp_f32_e32 v217, v131
	v_exp_f32_e32 v232, v132
	v_exp_f32_e32 v235, v133
	v_exp_f32_e32 v236, v134
	v_exp_f32_e32 v239, v135
	v_exp_f32_e32 v212, v136
	v_exp_f32_e32 v215, v137
	v_exp_f32_e32 v216, v138
	v_exp_f32_e32 v233, v139
	v_exp_f32_e32 v234, v140
	v_exp_f32_e32 v237, v141
	v_exp_f32_e32 v238, v142
	v_exp_f32_e32 v240, v143
	s_waitcnt vmcnt(4) lgkmcnt(0)
	s_barrier
	s_add_i32 s10, s39, 0x8000
	s_and_b32 s48, s10, 0x1ffff
	s_add_i32 s10, s48, 0
	v_add_u32_e32 v96, s10, v202
	ds_read_b128 v[242:245], v96 offset:24576
	ds_read_b128 v[96:99], v96 offset:16384
	v_add_u32_e32 v241, s10, v201
	v_exp_f32_e32 v112, v112
	v_exp_f32_e32 v115, v115
	v_exp_f32_e32 v116, v116
	s_waitcnt lgkmcnt(0)
	v_mfma_f32_32x32x16_bf16 v[128:143], v[96:99], v[158:161], v[80:95]
	v_exp_f32_e32 v117, v117
	v_exp_f32_e32 v118, v118
	v_mfma_f32_32x32x16_bf16 v[96:111], v[242:245], v[158:161], v[80:95]
	ds_read_b128 v[242:245], v241 offset:24576
	ds_read_b128 v[246:249], v241 offset:16384
	v_add_u32_e32 v241, s10, v199
	ds_read_b128 v[68:71], v241 offset:24576
	ds_read_b128 v[72:75], v241 offset:16384
	v_add_u32_e32 v241, s10, v183
	s_waitcnt lgkmcnt(2)
	v_mfma_f32_32x32x16_bf16 v[128:143], v[246:249], v[154:157], v[128:143]
	v_mfma_f32_32x32x16_bf16 v[96:111], v[242:245], v[154:157], v[96:111]
	ds_read_b128 v[242:245], v241 offset:24576
	ds_read_b128 v[246:249], v241 offset:16384
	s_waitcnt lgkmcnt(2)
	v_mfma_f32_32x32x16_bf16 v[128:143], v[72:75], v[150:153], v[128:143]
	v_mfma_f32_32x32x16_bf16 v[96:111], v[68:71], v[150:153], v[96:111]
	v_exp_f32_e32 v241, v113
	v_add_f32_e32 v113, 0, v211
	v_add_f32_e32 v113, v213, v113
	v_add_f32_e32 v113, v214, v113
	v_add_f32_e32 v113, v217, v113
	v_add_f32_e32 v113, v232, v113
	v_add_f32_e32 v113, v235, v113
	v_add_f32_e32 v113, v236, v113
	v_add_f32_e32 v113, v239, v113
	v_add_f32_e32 v113, v212, v113
	v_add_f32_e32 v113, v215, v113
	v_add_f32_e32 v113, v216, v113
	v_add_f32_e32 v113, v233, v113
	v_add_f32_e32 v113, v234, v113
	v_add_f32_e32 v113, v237, v113
	s_waitcnt lgkmcnt(0)
	v_mfma_f32_32x32x16_bf16 v[96:111], v[242:245], v[146:149], v[96:111]
	v_exp_f32_e32 v242, v114
	v_add_f32_e32 v113, v238, v113
	v_add_f32_e32 v113, v240, v113
	v_add_f32_e32 v113, v112, v113
	v_add_f32_e32 v113, v241, v113
	v_add_f32_e32 v113, v242, v113
	v_exp_f32_e32 v243, v119
	v_add_f32_e32 v113, v115, v113
	v_exp_f32_e32 v119, v120
	v_add_f32_e32 v113, v116, v113
	v_exp_f32_e32 v120, v121
	v_add_f32_e32 v113, v117, v113
	v_exp_f32_e32 v121, v122
	v_add_f32_e32 v113, v118, v113
	v_exp_f32_e32 v122, v123
	v_add_f32_e32 v113, v243, v113
	v_exp_f32_e32 v123, v124
	v_add_f32_e32 v113, v119, v113
	v_exp_f32_e32 v124, v125
	v_add_f32_e32 v113, v120, v113
	v_mfma_f32_32x32x16_bf16 v[128:143], v[246:249], v[146:149], v[128:143]
	v_exp_f32_e32 v125, v126
	v_add_f32_e32 v113, v121, v113
	v_exp_f32_e32 v126, v127
	v_add_f32_e32 v113, v122, v113
	v_add_f32_e32 v113, v123, v113
	v_add_f32_e32 v113, v124, v113
	v_add_f32_e32 v113, v125, v113
	v_add_f32_e32 v113, v126, v113
	v_mov_b32_e32 v114, v113
	s_nop 1
	v_permlane32_swap_b32_e32 v113, v114
	v_cvt_pk_bf16_f32 v250, v211, v213
	v_cvt_pk_bf16_f32 v251, v214, v217
	v_cvt_pk_bf16_f32 v252, v232, v235
	v_cvt_pk_bf16_f32 v253, v236, v239
	v_cvt_pk_bf16_f32 v212, v212, v215
	v_cvt_pk_bf16_f32 v213, v216, v233
	v_cvt_pk_bf16_f32 v214, v234, v237
	v_cvt_pk_bf16_f32 v215, v238, v240
	v_cvt_pk_bf16_f32 v232, v112, v241
	v_cvt_pk_bf16_f32 v233, v242, v115
	v_cvt_pk_bf16_f32 v234, v116, v117
	v_cvt_pk_bf16_f32 v235, v118, v243
	v_cvt_pk_bf16_f32 v116, v119, v120
	v_cvt_pk_bf16_f32 v117, v121, v122
	v_cvt_pk_bf16_f32 v118, v123, v124
	v_cvt_pk_bf16_f32 v119, v125, v126
	v_add_u32_e32 v112, s39, v205
	ds_read_b64_tr_b16 v[120:121], v112 offset:0
	ds_read_b64_tr_b16 v[122:123], v112 offset:0x800
	ds_read_b64_tr_b16 v[124:125], v112 offset:0x1000
	ds_read_b64_tr_b16 v[126:127], v112 offset:0x1800
	ds_read_b64_tr_b16 v[236:237], v112 offset:0x2000
	ds_read_b64_tr_b16 v[238:239], v112 offset:0x2800
	ds_read_b64_tr_b16 v[240:241], v112 offset:0x3000
	ds_read_b64_tr_b16 v[242:243], v112 offset:0x3800
	s_cmp_gt_u32 s44, 60
	s_cselect_b64 s[52:53], -1, 0
	s_and_b64 vcc, exec, s[52:53]
	s_cbranch_vccnz .LBB0_204
	s_add_i32 s10, s56, 0x8000
	s_and_b32 s10, s10, 0x1ffff
	s_add_i32 s12, s21, s10
	v_lshl_add_u64 v[174:175], v[174:175], 0, s[68:69]
	s_add_i32 m0, s12, 0x4000
	s_mov_b64 s[10:11], 0x4040000
	global_load_lds_dwordx4 v[174:175], off
	v_lshl_add_u64 v[174:175], v[172:173], 0, s[10:11]
	s_mov_b32 m0, s12
	s_mov_b64 s[10:11], 0x4040080
	global_load_lds_dwordx4 v[174:175], off
	v_lshl_add_u64 v[174:175], v[176:177], 0, s[68:69]
	s_add_i32 m0, s12, 0x4400
	v_lshl_add_u64 v[172:173], v[172:173], 0, s[10:11]
	global_load_lds_dwordx4 v[174:175], off
	s_add_i32 m0, s12, 0x400
	s_nop 0
	global_load_lds_dwordx4 v[172:173], off

; #define SBAR() __builtin_amdgcn_sched_barrier(0)
; __device__ __forceinline__ void unit(const bf16* Qb, const bf16* __restrict__ Kh, const bf16* __restrict__ Vh, bf16* Ob, float lam, float post, const float* __restrict__ gsub, char* lds) {
;     ...
;   for (int j = 1; j + 1 < NT; j += 2) {
;     A_STEP(pB0, pB1, pA0, pA1, alB, alA, j);
;     A_STEP(pA0, pA1, pB0, pB1, alA, alB, j + 1);
;   }
;   A_STEP(pB0, pB1, pA0, pA1, alB, alA, NT - 1);
;   finishSM(pB0, pB1, alB, l_reg, pa0, pa1, pa2, pa3); SBAR();
;   pv_d0(o, vb0 + sv, pa0, pa1, pa2, pa3);
.LBB0_217:
	v_mov_b64_e32 v[64:65], v[80:81]
	v_mov_b64_e32 v[66:67], v[82:83]
	v_mov_b64_e32 v[68:69], v[84:85]
	v_mov_b64_e32 v[70:71], v[86:87]
	v_mov_b64_e32 v[72:73], v[88:89]
	v_mov_b64_e32 v[74:75], v[90:91]
	v_mov_b64_e32 v[76:77], v[92:93]
	v_mov_b64_e32 v[78:79], v[94:95]
	v_or_b32_e32 v113, 0x2000, v182
	s_add_i32 s10, 0, 0x1c000
	v_add3_u32 v80, v204, v113, s10
	ds_read_b128 v[114:117], v80
	v_add_u32_e32 v80, s10, v202
	ds_read_b128 v[118:121], v80
	v_exp_f32_e32 v122, v105
	v_exp_f32_e32 v123, v106
	v_exp_f32_e32 v124, v107
	v_exp_f32_e32 v125, v108
	v_exp_f32_e32 v126, v109
	v_exp_f32_e32 v110, v110
	v_exp_f32_e32 v111, v111
	s_waitcnt lgkmcnt(0)
	v_mfma_f32_32x32x16_bf16 v[80:95], v[118:121], v[158:161], v[64:79]
	v_add_u32_e32 v118, s10, v201
	ds_read_b128 v[118:121], v118
	v_cvt_pk_bf16_f32 v105, v232, v234
	v_mfma_f32_32x32x16_bf16 v[64:79], v[114:117], v[158:161], v[64:79]
	v_add3_u32 v114, v203, v113, s10
	ds_read_b128 v[114:117], v114
	s_waitcnt lgkmcnt(0)
	v_mfma_f32_32x32x16_bf16 v[64:79], v[114:117], v[154:157], v[64:79]
	v_add3_u32 v114, v200, v113, s10
	ds_read_b128 v[114:117], v114
	v_add3_u32 v113, v198, v113, s10
	s_waitcnt lgkmcnt(0)
	v_mfma_f32_32x32x16_bf16 v[64:79], v[114:117], v[150:153], v[64:79]
	ds_read_b128 v[114:117], v113
	v_add_u32_e32 v113, s10, v183
	v_mfma_f32_32x32x16_bf16 v[80:95], v[118:121], v[154:157], v[80:95]
	v_add_u32_e32 v118, s10, v199
	ds_read_b128 v[118:121], v118
	s_waitcnt lgkmcnt(0)
	v_mfma_f32_32x32x16_bf16 v[80:95], v[118:121], v[150:153], v[80:95]
	ds_read_b128 v[118:121], v113
	v_exp_f32_e32 v113, v96
	v_add_f32_e32 v96, 0, v172
	v_add_f32_e32 v96, v174, v96
	v_add_f32_e32 v96, v175, v96
	v_add_f32_e32 v96, v211, v96
	v_add_f32_e32 v96, v212, v96
	v_add_f32_e32 v96, v215, v96
	v_add_f32_e32 v96, v216, v96
	v_add_f32_e32 v96, v233, v96
	v_add_f32_e32 v96, v173, v96
	v_add_f32_e32 v96, v176, v96
	v_add_f32_e32 v96, v177, v96
	v_add_f32_e32 v96, v213, v96
	v_add_f32_e32 v96, v214, v96
	v_mfma_f32_32x32x16_bf16 v[64:79], v[114:117], v[146:149], v[64:79]
	v_exp_f32_e32 v114, v97
	v_add_f32_e32 v96, v217, v96
	v_exp_f32_e32 v115, v98
	v_add_f32_e32 v96, v232, v96
	v_exp_f32_e32 v116, v99
	v_add_f32_e32 v96, v234, v96
	v_exp_f32_e32 v117, v100
	v_add_f32_e32 v96, v113, v96
	s_waitcnt lgkmcnt(0)
	v_mfma_f32_32x32x16_bf16 v[80:95], v[118:121], v[146:149], v[80:95]
	v_exp_f32_e32 v118, v101
	v_add_f32_e32 v96, v114, v96
	v_exp_f32_e32 v119, v102
	v_add_f32_e32 v96, v115, v96
	v_exp_f32_e32 v120, v103
	v_add_f32_e32 v96, v116, v96
	v_exp_f32_e32 v121, v104
	v_add_f32_e32 v96, v117, v96
	v_add_f32_e32 v96, v118, v96
	v_add_f32_e32 v96, v119, v96
	v_add_f32_e32 v96, v120, v96
	v_add_f32_e32 v96, v121, v96
	v_add_f32_e32 v96, v122, v96
	v_add_f32_e32 v96, v123, v96
	v_add_f32_e32 v96, v124, v96
	v_add_f32_e32 v96, v125, v96
	v_add_f32_e32 v96, v126, v96
	v_add_f32_e32 v96, v110, v96
	v_add_f32_e32 v96, v111, v96
	v_mov_b32_e32 v97, v96
	s_nop 1
	v_permlane32_swap_b32_e32 v96, v97
	v_cvt_pk_bf16_f32 v98, v172, v174
	v_cvt_pk_bf16_f32 v99, v175, v211
	v_cvt_pk_bf16_f32 v100, v212, v215
	v_cvt_pk_bf16_f32 v101, v216, v233
	v_cvt_pk_bf16_f32 v102, v173, v176
	v_cvt_pk_bf16_f32 v103, v177, v213
	v_cvt_pk_bf16_f32 v104, v214, v217
	v_cvt_pk_bf16_f32 v106, v113, v114
	v_cvt_pk_bf16_f32 v107, v115, v116
	v_cvt_pk_bf16_f32 v108, v117, v118
	v_cvt_pk_bf16_f32 v109, v119, v120
	v_cvt_pk_bf16_f32 v114, v121, v122
	v_cvt_pk_bf16_f32 v115, v123, v124
	v_cvt_pk_bf16_f32 v116, v125, v126
	v_cvt_pk_bf16_f32 v117, v110, v111
	s_cmp_lg_u32 0, -1
	s_cselect_b32 s10, 0, 0
	s_add_i32 s10, s10, 0x10000
	v_add_u32_e32 v110, s10, v181
	ds_read_b64_tr_b16 v[118:119], v110 offset:0
	ds_read_b64_tr_b16 v[120:121], v110 offset:0x800
	ds_read_b64_tr_b16 v[122:123], v110 offset:0x1000
	ds_read_b64_tr_b16 v[124:125], v110 offset:0x1800
	ds_read_b64_tr_b16 v[126:127], v110 offset:0x2000
	ds_read_b64_tr_b16 v[128:129], v110 offset:0x2800
	ds_read_b64_tr_b16 v[130:131], v110 offset:0x3000
	ds_read_b64_tr_b16 v[132:133], v110 offset:0x3800
	s_waitcnt lgkmcnt(0)
; #define SBAR() __builtin_amdgcn_sched_barrier(0)
; template <int OFF> __device__ __forceinline__ s16x4 tr_read(int vb) { s16x4 r; asm volatile("ds_read_b64_tr_b16 %0, %1 offset:%2" : "=&v"(r) : "v"(vb), "i"(OFF) : "memory"); return r; }
; template <bool FIRST> __device__ __forceinline__ void partialSM(f32x16& p0, f32x16& p1, float& m_reg, f32x16& negm, float& alpha) {
;   float pmax = p0[0];
; #pragma unroll
;   for (int r = 1; r < 16; ++r) pmax = fmaxf(pmax, p0[r]);
; #pragma unroll
;   for (int r = 0; r < 16; ++r) pmax = fmaxf(pmax, p1[r]);
;   { auto rr = __builtin_amdgcn_permlane32_swap(__float_as_uint(pmax), __float_as_uint(pmax), false, false);
;     pmax = fmaxf(__uint_as_float(rr[0]), __uint_as_float(rr[1])); }
;   alpha = 1.f;
;   if (FIRST || __builtin_expect(__any(pmax > THR), 0)) { const float dl = FIRST ? pmax : fmaxf(pmax, 0.f); m_reg += dl; if (!FIRST) alpha = __builtin_amdgcn_exp2f(-dl);
; template <int D0> __device__ __forceinline__ void pv_one(f32x16& od, int vb, bf16x8 pa0, bf16x8 pa1, bf16x8 pa2, bf16x8 pa3) {
;   const s16x4 l0 = tr_read<v_rd_off(D0, 0, 0)>(vb), h0 = tr_read<v_rd_off(D0, 0, 1)>(vb), l1 = tr_read<v_rd_off(D0, 1, 0)>(vb), h1 = tr_read<v_rd_off(D0, 1, 1)>(vb);
;   const s16x4 l2 = tr_read<v_rd_off(D0, 2, 0)>(vb), h2 = tr_read<v_rd_off(D0, 2, 1)>(vb), l3 = tr_read<v_rd_off(D0, 3, 0)>(vb), h3 = tr_read<v_rd_off(D0, 3, 1)>(vb);
;   asm volatile("s_waitcnt lgkmcnt(0)" ::: "memory"); SBAR();
;   od = __builtin_amdgcn_mfma_f32_32x32x16_bf16(pa0, ATT_PK(l0, h0), od, 0, 0, 0);
;   od = __builtin_amdgcn_mfma_f32_32x32x16_bf16(pa1, ATT_PK(l1, h1), od, 0, 0, 0);
;   od = __builtin_amdgcn_mfma_f32_32x32x16_bf16(pa2, ATT_PK(l2, h2), od, 0, 0, 0);
;   od = __builtin_amdgcn_mfma_f32_32x32x16_bf16(pa3, ATT_PK(l3, h3), od, 0, 0, 0);
; }
; __device__ __forceinline__ void pv_d0(f32x16* o, int vb, bf16x8 pa0, bf16x8 pa1, bf16x8 pa2, bf16x8 pa3) {
;   pv_one<0>(o[0], vb, pa0, pa1, pa2, pa3); pv_one<1>(o[1], vb, pa0, pa1, pa2, pa3); pv_one<2>(o[2], vb, pa0, pa1, pa2, pa3); pv_one<3>(o[3], vb, pa0, pa1, pa2, pa3);
; }
	s_nop 0
	v_mfma_f32_32x32x16_bf16 v[0:15], v[98:101], v[118:121], v[0:15]
	ds_read_b64_tr_b16 v[118:119], v110 offset:0x200
	ds_read_b64_tr_b16 v[120:121], v110 offset:0xa00
	v_mfma_f32_32x32x16_bf16 v[0:15], v[102:105], v[122:125], v[0:15]
	ds_read_b64_tr_b16 v[122:123], v110 offset:0x1200
	ds_read_b64_tr_b16 v[124:125], v110 offset:0x1a00
	v_mfma_f32_32x32x16_bf16 v[0:15], v[106:109], v[126:129], v[0:15]
	ds_read_b64_tr_b16 v[126:127], v110 offset:0x2200
	ds_read_b64_tr_b16 v[128:129], v110 offset:0x2a00
	v_mfma_f32_32x32x16_bf16 v[0:15], v[114:117], v[130:133], v[0:15]
	ds_read_b64_tr_b16 v[130:131], v110 offset:0x3200
	ds_read_b64_tr_b16 v[132:133], v110 offset:0x3a00
	s_waitcnt lgkmcnt(0)
	v_mfma_f32_32x32x16_bf16 v[48:63], v[98:101], v[118:121], v[48:63]
	ds_read_b64_tr_b16 v[118:119], v110 offset:0x400
	ds_read_b64_tr_b16 v[120:121], v110 offset:0xc00
	v_mfma_f32_32x32x16_bf16 v[48:63], v[102:105], v[122:125], v[48:63]
	ds_read_b64_tr_b16 v[122:123], v110 offset:0x1400
	ds_read_b64_tr_b16 v[124:125], v110 offset:0x1c00
	v_mfma_f32_32x32x16_bf16 v[48:63], v[106:109], v[126:129], v[48:63]
	ds_read_b64_tr_b16 v[126:127], v110 offset:0x2400
	ds_read_b64_tr_b16 v[128:129], v110 offset:0x2c00
	v_mfma_f32_32x32x16_bf16 v[48:63], v[114:117], v[130:133], v[48:63]
	ds_read_b64_tr_b16 v[130:131], v110 offset:0x3400
	ds_read_b64_tr_b16 v[132:133], v110 offset:0x3c00
	s_waitcnt lgkmcnt(0)
	v_mfma_f32_32x32x16_bf16 v[32:47], v[98:101], v[118:121], v[32:47]
	ds_read_b64_tr_b16 v[118:119], v110 offset:0x600
	ds_read_b64_tr_b16 v[120:121], v110 offset:0xe00
	v_mfma_f32_32x32x16_bf16 v[32:47], v[102:105], v[122:125], v[32:47]
	ds_read_b64_tr_b16 v[122:123], v110 offset:0x1600
	ds_read_b64_tr_b16 v[124:125], v110 offset:0x1e00
	v_mfma_f32_32x32x16_bf16 v[32:47], v[106:109], v[126:129], v[32:47]
	ds_read_b64_tr_b16 v[126:127], v110 offset:0x2600
	ds_read_b64_tr_b16 v[128:129], v110 offset:0x2e00
	v_mfma_f32_32x32x16_bf16 v[32:47], v[114:117], v[130:133], v[32:47]
	ds_read_b64_tr_b16 v[130:131], v110 offset:0x3600
	ds_read_b64_tr_b16 v[132:133], v110 offset:0x3e00
	s_waitcnt lgkmcnt(0)
	v_mfma_f32_32x32x16_bf16 v[16:31], v[98:101], v[118:121], v[16:31]
	v_max_f32_e32 v98, v81, v81
	v_max_f32_e32 v99, v80, v80
	v_max_f32_e32 v98, v99, v98
	v_max3_f32 v98, v98, v82, v83
	v_max3_f32 v98, v98, v84, v85
	v_max3_f32 v98, v98, v86, v87
	v_max3_f32 v98, v98, v88, v89
	v_mfma_f32_32x32x16_bf16 v[16:31], v[102:105], v[122:125], v[16:31]
	v_max3_f32 v98, v98, v90, v91
	v_max3_f32 v98, v98, v92, v93
	v_max3_f32 v98, v98, v94, v95
	v_max3_f32 v98, v98, v64, v65
	v_max3_f32 v98, v98, v66, v67
	v_max3_f32 v98, v98, v68, v69
	v_max3_f32 v98, v98, v70, v71
	v_mfma_f32_32x32x16_bf16 v[16:31], v[106:109], v[126:129], v[16:31]
	v_max3_f32 v98, v98, v72, v73
	v_max3_f32 v98, v98, v74, v75
	v_max3_f32 v98, v98, v76, v77
	v_max3_f32 v98, v98, v78, v79
	v_mov_b32_e32 v99, v98
	s_nop 1
	v_permlane32_swap_b32_e32 v98, v99
	v_mfma_f32_32x32x16_bf16 v[16:31], v[114:117], v[130:133], v[16:31]
	v_max_f32_e32 v99, v99, v99
	v_max_f32_e32 v98, v98, v98
	v_max_f32_e32 v99, v98, v99
	v_cmp_lt_f32_e32 vcc, s19, v99
	v_mov_b32_e32 v98, 1.0
	s_cbranch_vccnz .LBB0_224
	v_cmp_gt_f32_e32 vcc, 1.0, v98
	s_cbranch_vccz .LBB0_222
